# plus: attention next-tile load addresses from per-item lane bases plus scalar tile offset (10 fewer VALU per tile)
# baseline (speedup 1.0000x reference)
.LBB0_574:
	s_lshl_b32 s40, s2, 8
	s_lshl_b32 s0, s10, 8
	s_add_i32 s40, s40, s14
	s_and_b32 s7, s0, 0x3000
	v_and_b32_e32 v10, 15, v4
	s_and_b32 s6, s10, 15
	s_add_i32 s0, s40, s7
	v_or_b32_e32 v0, s0, v10
	s_mul_i32 s0, s6, 0x180
	v_bfe_u32 v11, v4, 4, 2
	s_add_u32 s0, s52, s0
	s_addc_u32 s1, s53, 0
	v_lshlrev_b32_e32 v2, 4, v11
	v_mov_b32_e32 v3, v1
	v_lshl_add_u64 v[6:7], s[0:1], 0, v[2:3]
	v_or_b32_e32 v188, 16, v0
	v_mad_u64_u32 v[8:9], s[0:1], v0, s31, v[6:7]
	v_mad_u64_u32 v[6:7], s[0:1], v188, s31, v[6:7]
	s_lshl_b32 s41, s2, 2
	s_lshl_b32 s0, s7, 12
	s_add_u32 s0, s56, s0
	s_addc_u32 s1, s57, 0
	s_lshl_b32 s11, s6, 7
	s_lshl_b32 s2, s6, 8
	s_add_u32 s0, s0, s2
	s_addc_u32 s1, s1, 0
	v_lshlrev_b32_e32 v192, 4, v10
	v_mov_b32_e32 v193, v1
	v_lshl_add_u64 v[194:195], s[0:1], 0, v[192:193]
	s_lshl_b32 s0, s7, 7
	s_add_u32 s0, s18, s0
	v_lshlrev_b32_e32 v3, 4, v4
	s_addc_u32 s1, s19, 0
	v_and_b32_e32 v196, 0x70, v3
	v_mov_b32_e32 v197, v1
	v_lshl_add_u64 v[198:199], s[0:1], 0, v[196:197]
	s_lshl_b32 s0, s6, 22
	s_add_u32 s0, s60, s0
	v_ashrrev_i32_e32 v190, 4, v4
	s_addc_u32 s1, s61, 0
	s_lshl_b32 s2, s7, 1
	s_add_u32 s0, s0, s2
	v_ashrrev_i32_e32 v191, 31, v190
	global_load_dwordx4 v[86:89], v[8:9], off
	global_load_dwordx4 v[82:85], v[8:9], off offset:64
	global_load_dwordx4 v[78:81], v[8:9], off offset:128
	global_load_dwordx4 v[74:77], v[8:9], off offset:192
	global_load_dwordx4 v[70:73], v[8:9], off offset:256
	global_load_dwordx4 v[66:69], v[8:9], off offset:320
	s_addc_u32 s1, s1, 0
	v_lshlrev_b64 v[8:9], 12, v[190:191]
	global_load_dwordx4 v[110:113], v[6:7], off
	global_load_dwordx4 v[106:109], v[6:7], off offset:64
	global_load_dwordx4 v[102:105], v[6:7], off offset:128
	global_load_dwordx4 v[98:101], v[6:7], off offset:192
	global_load_dwordx4 v[94:97], v[6:7], off offset:256
	global_load_dwordx4 v[90:93], v[6:7], off offset:320
	v_ashrrev_i32_e32 v6, 3, v4
	v_lshl_add_u64 v[4:5], s[0:1], 0, v[196:197]
	v_lshl_add_u64 v[8:9], v[194:195], 0, v[8:9]
	s_mov_b32 s0, 0x20000
	global_load_dwordx4 v[114:117], v[8:9], off
	v_add_co_u32_e32 v8, vcc, s0, v8
	v_ashrrev_i32_e32 v7, 31, v6
	s_nop 0
	v_addc_co_u32_e32 v9, vcc, 0, v9, vcc
	global_load_dwordx4 v[118:121], v[8:9], off
	v_lshlrev_b64 v[8:9], 7, v[6:7]
	v_lshl_add_u64 v[8:9], v[198:199], 0, v[8:9]
	v_add_u32_e32 v202, 64, v6
	global_load_dwordx4 v[122:125], v[8:9], off
	v_lshlrev_b64 v[8:9], 15, v[6:7]
	v_ashrrev_i32_e32 v203, 31, v202
	v_lshl_add_u64 v[200:201], v[4:5], 0, v[8:9]
	v_lshlrev_b64 v[8:9], 15, v[202:203]
	v_lshl_add_u64 v[204:205], v[4:5], 0, v[8:9]
	global_load_dwordx4 v[126:129], v[200:201], off
	global_load_dwordx4 v[130:133], v[204:205], off
	s_movk_i32 s1, 0x190
	v_mul_lo_u32 v216, v190, s1
	v_add3_u32 v3, 0, v216, v192
	v_mul_lo_u32 v218, v6, s1
	v_lshlrev_b32_e32 v4, 8, v6
	s_movk_i32 s0, 0x90
	v_mov_b32_e32 v5, v1
	v_mul_lo_u32 v221, v6, s0
	v_lshlrev_b32_e32 v193, 2, v11
	v_or_b32_e32 v219, s40, v10
	v_mov_b32_e32 v189, v1
	s_mov_b32 s42, 0
	v_add_u32_e32 v217, 0x3200, v216
	v_add_u32_e32 v222, 0x2400, v221
	s_or_b32 s43, s40, 31
	v_or_b32_e32 v215, 16, v219
	s_or_b32 s46, s41, 3
	v_mov_b32_e32 v191, 0
	v_mov_b32_e32 v208, 0xf149f2ca
	s_mov_b32 s47, 0
	v_mov_b32_e32 v206, 0xf149f2ca
	v_mov_b32_e32 v203, 0
	s_waitcnt vmcnt(4)
	ds_write_b128 v3, v[114:117]
	s_waitcnt vmcnt(3)
	ds_write_b128 v3, v[118:121] offset:12800
	v_add3_u32 v3, 0, v218, v196
	s_waitcnt vmcnt(2)
	ds_write_b128 v3, v[122:125] offset:256
	v_sub_u32_e32 v3, v3, v4
	v_mov_b32_e32 v4, v1
	s_waitcnt vmcnt(1)
	ds_write_b128 v3, v[126:129] offset:51200
	s_waitcnt vmcnt(0)
	ds_write_b128 v3, v[130:133] offset:60416
	v_mad_u32_u24 v3, v10, s1, 0
	v_add_u32_e32 v220, v3, v2
	v_lshlrev_b32_e32 v2, 8, v10
	v_sub_u32_e32 v2, v3, v2
	v_lshl_add_u32 v197, v11, 3, v2
	v_mov_b32_e32 v2, v1
	v_mov_b32_e32 v3, v1
	v_mov_b64_e32 v[8:9], v[4:5]
	v_mov_b64_e32 v[12:13], v[4:5]
	v_mov_b64_e32 v[16:17], v[4:5]
	v_mov_b64_e32 v[20:21], v[4:5]
	v_mov_b64_e32 v[24:25], v[4:5]
	v_mov_b64_e32 v[28:29], v[4:5]
	v_mov_b64_e32 v[32:33], v[4:5]
	v_mov_b64_e32 v[36:37], v[4:5]
	v_mov_b64_e32 v[40:41], v[4:5]
	v_mov_b64_e32 v[44:45], v[4:5]
	v_mov_b64_e32 v[48:49], v[4:5]
	v_mov_b64_e32 v[52:53], v[4:5]
	v_mov_b64_e32 v[56:57], v[4:5]
	v_mov_b64_e32 v[60:61], v[4:5]
	v_mov_b64_e32 v[64:65], v[4:5]
	v_mov_b64_e32 v[6:7], v[2:3]
	v_mov_b64_e32 v[10:11], v[2:3]
	v_mov_b64_e32 v[14:15], v[2:3]
	v_mov_b64_e32 v[18:19], v[2:3]
	v_mov_b64_e32 v[22:23], v[2:3]
	v_mov_b64_e32 v[26:27], v[2:3]
	v_mov_b64_e32 v[30:31], v[2:3]
	v_mov_b64_e32 v[34:35], v[2:3]
	v_mov_b64_e32 v[38:39], v[2:3]
	v_mov_b64_e32 v[42:43], v[2:3]
	v_mov_b64_e32 v[46:47], v[2:3]
	v_mov_b64_e32 v[50:51], v[2:3]
	v_mov_b64_e32 v[54:55], v[2:3]
	v_mov_b64_e32 v[58:59], v[2:3]
	v_mov_b64_e32 v[62:63], v[2:3]
	v_lshlrev_b32_e32 v244, 12, v190
	v_mov_b32_e32 v245, 0
	v_lshl_add_u64 v[244:245], v[194:195], 0, v[244:245]
	v_mov_b32_e32 v246, 0x20000
	v_mov_b32_e32 v247, 0
	v_lshl_add_u64 v[246:247], v[244:245], 0, v[246:247]
	v_add_u32_e32 v248, 0xffffffc0, v202
	v_lshlrev_b32_e32 v248, 7, v248
	v_mov_b32_e32 v249, 0
	v_lshl_add_u64 v[248:249], v[198:199], 0, v[248:249]
	s_waitcnt lgkmcnt(0)
	s_barrier

.LBB0_578:
	s_nop 0
	s_add_i32 s58, s47, 64
	s_lshl_b64 s[0:1], s[58:59], 12
	v_lshl_add_u64 v[114:115], v[244:245], 0, s[0:1]
	v_lshl_add_u64 v[118:119], v[246:247], 0, s[0:1]
	s_lshl_b64 s[0:1], s[58:59], 7
	v_lshl_add_u64 v[122:123], v[248:249], 0, s[0:1]
	s_lshl_b64 s[0:1], s[58:59], 1
	v_lshl_add_u64 v[126:127], v[200:201], 0, s[0:1]
	v_lshl_add_u64 v[130:131], v[204:205], 0, s[0:1]
	global_load_dwordx4 v[114:117], v[114:115], off
	s_nop 0
	global_load_dwordx4 v[118:121], v[118:119], off
	s_nop 0
	global_load_dwordx4 v[122:125], v[122:123], off
	s_nop 0
	global_load_dwordx4 v[126:129], v[126:127], off
	v_max_f32_e32 v223, v151, v151
	global_load_dwordx4 v[130:133], v[130:131], off
	v_max_f32_e32 v224, v150, v150
	v_max_f32_e32 v223, v224, v223
	v_max3_f32 v223, v223, v152, v153
	v_max3_f32 v223, v223, v154, v155
	v_max3_f32 v223, v223, v156, v157
	v_max3_f32 v223, v223, v158, v159
	v_max3_f32 v223, v223, v160, v161
	v_max3_f32 v223, v223, v162, v163
	v_max3_f32 v223, v223, v164, v165
	v_mov_b32_e32 v224, v223
	s_waitcnt lgkmcnt(0)
	s_nop 0
	v_permlane16_swap_b32_e32 v223, v224
	v_max_f32_e32 v223, v223, v224
	v_mov_b32_e32 v224, v223
	s_nop 1
	v_permlane32_swap_b32_e32 v223, v224
	v_max3_f32 v223, v206, v223, v224
	v_sub_f32_e32 v206, v206, v223
	v_exp_f32_e32 v206, v206
	s_nop 0
	v_cmp_neq_f32_e32 vcc, 1.0, v206
	s_cbranch_vccz .LBB0_580
	v_pk_mul_f32 v[64:65], v[64:65], v[206:207] op_sel_hi:[1,0]
	v_pk_mul_f32 v[62:63], v[62:63], v[206:207] op_sel_hi:[1,0]
	v_pk_mul_f32 v[60:61], v[60:61], v[206:207] op_sel_hi:[1,0]
	v_pk_mul_f32 v[58:59], v[58:59], v[206:207] op_sel_hi:[1,0]
	v_pk_mul_f32 v[56:57], v[56:57], v[206:207] op_sel_hi:[1,0]
	v_pk_mul_f32 v[54:55], v[54:55], v[206:207] op_sel_hi:[1,0]
	v_pk_mul_f32 v[52:53], v[52:53], v[206:207] op_sel_hi:[1,0]
	v_pk_mul_f32 v[50:51], v[50:51], v[206:207] op_sel_hi:[1,0]
	v_pk_mul_f32 v[48:49], v[48:49], v[206:207] op_sel_hi:[1,0]
	v_pk_mul_f32 v[46:47], v[46:47], v[206:207] op_sel_hi:[1,0]
	v_pk_mul_f32 v[44:45], v[44:45], v[206:207] op_sel_hi:[1,0]
	v_pk_mul_f32 v[42:43], v[42:43], v[206:207] op_sel_hi:[1,0]
	v_pk_mul_f32 v[40:41], v[40:41], v[206:207] op_sel_hi:[1,0]
	v_pk_mul_f32 v[38:39], v[38:39], v[206:207] op_sel_hi:[1,0]
	v_pk_mul_f32 v[36:37], v[36:37], v[206:207] op_sel_hi:[1,0]
	v_pk_mul_f32 v[34:35], v[34:35], v[206:207] op_sel_hi:[1,0]
